# v87 + mixer transpose items: LDS-free dwordx4-load/16-byte-store transpose replaces the LDS-staged 2-byte-store version
# speedup vs baseline: 1.0139x; 1.0024x over previous
.LBB0_98:
	s_or_b64 exec, exec, s[0:1]
	v_readlane_b32 s0, v253, 61
	s_waitcnt lgkmcnt(0)
	s_barrier
	v_mov_b32_e32 v0, s0
	ds_read_b32 v0, v0
	s_mov_b64 s[0:1], -1
	s_waitcnt lgkmcnt(0)
	v_cmp_le_i32_e32 vcc, s94, v0
	v_readfirstlane_b32 s46, v0
	s_cbranch_vccnz .LBB0_93
	s_cmpk_lt_i32 s46, 0x100
	s_cselect_b64 s[0:1], -1, 0
	v_mov_b32_e32 v168, v155
	s_and_b64 vcc, exec, s[0:1]
	s_cbranch_vccnz .LBB0_244
	s_cmp_lt_i32 s46, s37
	s_cselect_b64 s[0:1], -1, 0
	s_cmp_ge_i32 s46, s41
	s_cselect_b64 s[2:3], -1, 0
	s_or_b64 s[2:3], s[0:1], s[2:3]
	s_mov_b64 s[0:1], -1
	s_and_b64 vcc, exec, s[2:3]
	s_cbranch_vccz .LBB0_244
	s_cmpk_gt_u32 s46, 0x2ff
	s_cbranch_scc0 .LBB0_227
	s_cmpk_gt_u32 s46, 0x4ff
	s_cbranch_scc0 .LBB0_158
	s_cmp_ge_i32 s46, s37
	s_cbranch_scc0 .LBB0_153
	s_cmp_ge_i32 s46, s92
	s_cbranch_scc0 .LBB0_138
	s_cmp_ge_i32 s46, s93
	s_cbranch_scc0 .LBB0_122
	s_sub_i32 s10, s46, s93
	v_readlane_b32 s32, v254, 57
	s_add_i32 s32, s32, 1
	s_sub_u32 s98, s96, 0xd0
	s_subb_u32 s99, s97, 0
	v_readfirstlane_b32 s58, v155
	s_lshr_b32 s58, s58, 6
	v_and_b32_e32 v102, 63, v155
	v_lshlrev_b32_e32 v103, 4, v102
	s_cmp_lt_u32 s10, 0x80
	s_cbranch_scc0 .Lmy_tm_s1
	s_load_dwordx2 s[72:73], s[98:99], 0x40
	s_lshr_b32 s11, s10, 3
	s_and_b32 s13, s10, 7
	s_mul_i32 s20, s32, 0x900000
	s_add_u32 s20, s20, 0x400
	s_mul_i32 s56, s32, 0x500000
	s_add_u32 s56, s56, 0x500000
	s_movk_i32 s4, 0x2400
	s_movk_i32 s6, 0x800
	s_mov_b32 s57, 13
	s_branch .Lmy_tm_sd
	s_nop 0
	s_nop 0
	s_nop 0
	s_nop 0
	s_nop 0
	s_nop 0
	s_nop 0
	s_nop 0
	s_nop 0
	s_nop 0
	s_nop 0
	s_nop 0
	s_nop 0
	s_nop 0
	s_nop 0
	s_nop 0
	s_nop 0
	s_nop 0
	s_nop 0
	s_nop 0
	s_nop 0
	s_nop 0
	s_nop 0
	s_nop 0
	s_nop 0
	s_nop 0
	s_nop 0
	s_nop 0
	s_nop 0
	s_nop 0
	s_nop 0
	s_nop 0
	s_nop 0
	s_nop 0
	s_nop 0
	s_nop 0
	s_nop 0
	s_nop 0
	s_nop 0
	s_nop 0
	s_nop 0
	s_nop 0
	s_nop 0
	s_nop 0
	s_nop 0
	s_nop 0
	s_nop 0
	s_nop 0
	s_nop 0
	s_nop 0
	s_nop 0
	s_nop 0
	s_nop 0
	s_nop 0
	s_nop 0
	s_nop 0
	s_nop 0
	s_nop 0
	s_nop 0
	s_nop 0
	s_nop 0
	s_nop 0
	s_nop 0
.Lmy_tm_s1:
	s_cmp_lt_u32 s10, 0xc0
	s_cbranch_scc0 .Lmy_tm_s2
	s_load_dwordx2 s[72:73], s[98:99], 0x48
	s_sub_i32 s10, s10, 0x80
	s_lshr_b32 s11, s10, 2
	s_and_b32 s13, s10, 3
	s_lshl_b32 s20, s32, 22
	s_lshl_b32 s56, s32, 21
	s_add_u32 s56, s56, 0x1800000
	s_movk_i32 s4, 0x1000
	s_movk_i32 s6, 0x800
	s_mov_b32 s57, 13
	s_branch .Lmy_tm_sd
.Lmy_tm_s2:
	s_cmp_lt_u32 s10, 0x1c0
	s_cbranch_scc0 .Lmy_tm_s3
	s_load_dwordx2 s[72:73], s[98:99], 0xa0
	s_sub_i32 s10, s10, 0xc0
	s_lshr_b32 s11, s10, 4
	s_and_b32 s13, s10, 15
	s_lshl_b32 s20, s32, 24
	s_lshl_b32 s56, s32, 23
	s_add_u32 s56, s56, 0x2000000
	s_movk_i32 s4, 0x4000
	s_movk_i32 s6, 0x800
	s_mov_b32 s57, 13
	s_branch .Lmy_tm_sd
.Lmy_tm_s3:
	s_load_dwordx2 s[72:73], s[98:99], 0xa8
	s_sub_i32 s10, s10, 0x1c0
	s_lshr_b32 s11, s10, 2
	s_and_b32 s13, s10, 3
	s_lshl_b32 s20, s32, 24
	s_lshl_b32 s56, s32, 23
	s_add_u32 s56, s56, 0x4000000
	s_movk_i32 s4, 0x1000
	s_movk_i32 s6, 0x2000
	s_mov_b32 s57, 15
.Lmy_tm_sd:
	s_add_u32 s2, s88, s56
	s_addc_u32 s3, s89, 0
	s_lshl_b32 s56, s13, 8
	s_mul_i32 s56, s56, s6
	s_lshl_b32 s0, s11, 7
	s_add_u32 s56, s56, s0
	s_lshl_b32 s0, s58, 4
	s_add_u32 s56, s56, s0
	s_add_u32 s2, s2, s56
	s_addc_u32 s3, s3, 0
	s_lshl_b32 s0, s11, 6
	s_lshl_b32 s56, s58, 3
	s_add_u32 s0, s0, s56
	s_mul_i32 s0, s0, s4
	s_lshl_b32 s56, s13, 10
	s_add_u32 s0, s0, s56
	s_add_u32 s20, s20, s0
	v_lshlrev_b32_e32 v104, s57, v102
	s_waitcnt lgkmcnt(0)
	s_add_u32 s0, s72, s20
	s_addc_u32 s1, s73, 0
	global_load_dwordx4 v[118:121], v103, s[0:1] nt
	s_add_u32 s0, s0, s4
	s_addc_u32 s1, s1, 0
	global_load_dwordx4 v[122:125], v103, s[0:1] nt
	s_add_u32 s0, s0, s4
	s_addc_u32 s1, s1, 0
	global_load_dwordx4 v[126:129], v103, s[0:1] nt
	s_add_u32 s0, s0, s4
	s_addc_u32 s1, s1, 0
	global_load_dwordx4 v[130:133], v103, s[0:1] nt
	s_add_u32 s0, s0, s4
	s_addc_u32 s1, s1, 0
	global_load_dwordx4 v[134:137], v103, s[0:1] nt
	s_add_u32 s0, s0, s4
	s_addc_u32 s1, s1, 0
	global_load_dwordx4 v[138:141], v103, s[0:1] nt
	s_add_u32 s0, s0, s4
	s_addc_u32 s1, s1, 0
	global_load_dwordx4 v[142:145], v103, s[0:1] nt
	s_add_u32 s0, s0, s4
	s_addc_u32 s1, s1, 0
	global_load_dwordx4 v[146:149], v103, s[0:1] nt
	s_waitcnt vmcnt(0)
	v_cvt_pk_bf16_f32 v80, v118, v122
	v_cvt_pk_bf16_f32 v81, v126, v130
	v_cvt_pk_bf16_f32 v82, v134, v138
	v_cvt_pk_bf16_f32 v83, v142, v146
	v_cvt_pk_bf16_f32 v84, v119, v123
	v_cvt_pk_bf16_f32 v85, v127, v131
	v_cvt_pk_bf16_f32 v86, v135, v139
	v_cvt_pk_bf16_f32 v87, v143, v147
	v_cvt_pk_bf16_f32 v88, v120, v124
	v_cvt_pk_bf16_f32 v89, v128, v132
	v_cvt_pk_bf16_f32 v90, v136, v140
	v_cvt_pk_bf16_f32 v91, v144, v148
	v_cvt_pk_bf16_f32 v92, v121, v125
	v_cvt_pk_bf16_f32 v93, v129, v133
	v_cvt_pk_bf16_f32 v94, v137, v141
	v_cvt_pk_bf16_f32 v95, v145, v149
	global_store_dwordx4 v104, v[80:83], s[2:3]
	s_add_u32 s2, s2, s6
	s_addc_u32 s3, s3, 0
	global_store_dwordx4 v104, v[84:87], s[2:3]
	s_add_u32 s2, s2, s6
	s_addc_u32 s3, s3, 0
	global_store_dwordx4 v104, v[88:91], s[2:3]
	s_add_u32 s2, s2, s6
	s_addc_u32 s3, s3, 0
	global_store_dwordx4 v104, v[92:95], s[2:3]
	s_mov_b64 s[0:1], 0
	s_mov_b32 s13, 0x800000
	s_mov_b64 s[10:11], 0x8000
